# v020 with one static s_setprio 1 for waves 4-7 at the phase latch and the 48 per-segment GEMM K-loop priority toggles removed
# baseline (speedup 1.0000x reference)
; __global__ void __launch_bounds__(512, 2) fwd_megakernel(Args a) {
;     ...
;     for (int ph = ph_lo; ph < ph_hi; ++ph) {
;         const int kind_ = ph == 0 ? -1 : (ph - 1) % 12;
;         if (kind_ == 2 || kind_ == 8 || kind_ == 11 || kind_ == 6) continue;
;         if (ph > ph_lo) { if (ph == ph_lo + 1 && ph_lo != 0) grid.sync(); else xcd_barrier(xbar); if (PROBE_DUP & 32) xcd_barrier(xbar); }
;         const int nrep = ((kind_ == -1 && (PROBE_DUP & 1)) || ((kind_ == 0 || kind_ == 9) && (PROBE_DUP & 2)) || (kind_ == 3 && (PROBE_DUP & 4)) || (kind_ == 5 && (PROBE_DUP & 8)) || (kind_ == 6 && (PROBE_DUP & 16))) ? 2 : 1;
;         for (int rep = 0; rep < nrep; ++rep) {
;         const __attribute__((address_space(4))) Args* ap = (const __attribute__((address_space(4))) Args*)__builtin_amdgcn_kernarg_segment_ptr();
;         asm volatile("" : "+s"(ap) :: "memory");
;     ...
;         int lane_; asm volatile("v_mbcnt_lo_u32_b32 %0, -1, 0\n\tv_mbcnt_hi_u32_b32 %0, -1, %0" : "=v"(lane_));
;         int tid = wave_s * 64 + lane_; asm volatile("" : "+v"(tid));
;         const int lane = tid & 63, wave = __builtin_amdgcn_readfirstlane(tid >> 6);
;         const int G = gridDim.x, gw = blockIdx.x * 8 + wave, NGW = G * 8;
.LBB0_9:
	v_readfirstlane_b32 s98, v200
	s_cmp_ge_u32 s98, 0x100
	s_cbranch_scc0 .Lprio_lead
	s_setprio 1

; #define PG8_STAGE(bufoff, gbase, voff) do { _Pragma("unroll") for (int _i = 0; _i < 2; ++_i) \
;         __builtin_amdgcn_global_load_lds((const unsigned*)((const char*)(gbase) + (voff)[_i]), (PG8_LAS unsigned*)(lds + (bufoff) + ldsw + _i * 8192), 16, 0, 0); } while (0)
; #define PG8_LDA(dst, b, h) do { if (PG8_MSK && !(mk & (3 << (2 * (h))))) break; _Pragma("unroll") for (int m = 0; m < 4; ++m) _Pragma("unroll") for (int k = 0; k < 2; ++k) dst[m][k] = *(const PG8_LAS bf16x8*)(lds + PG8_SA(b, h) + aoff + m * 2048 + k * 1024); } while (0)
; #define PG8_BAR __builtin_amdgcn_s_barrier()
; template <class Epi, class Sched, bool ALIGN_EPI = false, bool SP2 = false>
; __device__ __forceinline__ void gemm_phase(PG8_LAS unsigned char* lds, const Gemm g, const Sched& S, const Epi& E, const int tid) {
;     ...
;         for (int t = 0; t < nt; t += 2) {
;             const bool last = (t == nt - 2);
;             if constexpr (Epi::MID) { if (E.use_rs && t == (nt >> 1)) E.mid(acc, cur, wr, fr); }
;             const char* a1 = cA + (size_t)(t + 1) * kstep;
;             const char* a2 = last ? nA : cA + (size_t)(t + 2) * kstep; const char* b2 = last ? nB : cB + (size_t)(t + 2) * kstep;
;             const char* a3 = a2 + kstep; const char* b3 = b2 + kstep;
;             if (last && has_next) S.a_ready(nxt);
;             if constexpr (SP2) {
;             PG8_LDB(B0, 0, 0); PG8_LDB(B1, 0, 1); PG8_SCHED; PG8_LDA(At, 0, 0); PG8_STAGE(PG8_SA(1, 1), a1 + hstep, voffA);
;             PG8_WAIT_V(8); PG8_WAIT_L(0); PG8_BAR; PG8_MMA(0, 0, At, B0); PG8_MMA(0, 1, At, B1); PG8_BAR; PG8_SCHED;
;             PG8_LDA(At, 0, 1); PG8_STAGE(PG8_SB(0, 0), b2, voffB); PG8_STAGE(PG8_SB(0, 1), b2 + hstep, voffB); PG8_STAGE(PG8_SA(0, 0), a2, voffA);
;             PG8_WAIT_V(8); PG8_WAIT_L(0); PG8_BAR; PG8_MMA(1, 0, At, B0); PG8_MMA(1, 1, At, B1); PG8_BAR; PG8_SCHED;
;             PG8_LDB(B0, 1, 0); PG8_LDB(B1, 1, 1); PG8_SCHED; PG8_LDA(At, 1, 0); PG8_STAGE(PG8_SA(0, 1), a2 + hstep, voffA);
;             PG8_WAIT_V(8); PG8_WAIT_L(0); PG8_BAR; PG8_MMA(0, 0, At, B0); PG8_MMA(0, 1, At, B1); PG8_BAR; PG8_SCHED;
;             PG8_LDA(At, 1, 1); PG8_STAGE(PG8_SB(1, 0), b3, voffB); PG8_STAGE(PG8_SB(1, 1), b3 + hstep, voffB); PG8_STAGE(PG8_SA(1, 0), a3, voffA);
;             PG8_WAIT_V(8); PG8_WAIT_L(0); PG8_BAR; PG8_MMA(1, 0, At, B0); PG8_MMA(1, 1, At, B1); PG8_BAR; PG8_SCHED;
.LBB0_338:
	s_add_u32 s44, s42, 0xfff80080
	s_addc_u32 s45, s43, -1
	s_add_i32 s48, 0, 0x10000
	s_cmp_eq_u32 s41, 28
	s_cselect_b32 s47, s1, s45
	s_cselect_b32 s46, s13, s44
	v_add_u32_e32 v140, s48, v143
	s_cselect_b32 s45, s11, s39
	s_cselect_b32 s44, s14, s15
	s_add_i32 s50, 0, 0x14000
	ds_read_b128 v[146:149], v140
	ds_read_b128 v[150:153], v140 offset:1024
	ds_read_b128 v[154:157], v140 offset:2048
	ds_read_b128 v[158:161], v140 offset:3072
	v_add_u32_e32 v140, s50, v143
	ds_read_b128 v[162:165], v140
	ds_read_b128 v[166:169], v140 offset:1024
	ds_read_b128 v[170:173], v140 offset:2048
	ds_read_b128 v[174:177], v140 offset:3072
	v_lshl_add_u64 v[140:141], s[42:43], 0, v[136:137]
	s_add_i32 m0, s25, 0xc000
	ds_read_b128 v[178:181], v145
	ds_read_b128 v[182:185], v145 offset:1024
	ds_read_b128 v[186:189], v145 offset:2048
	ds_read_b128 v[190:193], v145 offset:3072
	ds_read_b128 v[194:197], v145 offset:4096
	ds_read_b128 v[204:207], v145 offset:5120
	ds_read_b128 v[208:211], v145 offset:6144
	ds_read_b128 v[212:215], v145 offset:7168
	global_load_lds_dwordx4 v[140:141], off
	v_lshl_add_u64 v[140:141], s[42:43], 0, v[138:139]
	s_add_i32 m0, s25, 0xe000
	s_nop 0
	global_load_lds_dwordx4 v[140:141], off
	s_waitcnt vmcnt(8)
	s_waitcnt lgkmcnt(0)
	s_barrier
	s_waitcnt lgkmcnt(0)
	v_mfma_f32_16x16x32_bf16 v[126:129], v[146:149], v[178:181], v[126:129]
	v_mfma_f32_16x16x32_bf16 v[122:125], v[154:157], v[178:181], v[122:125]
	v_mfma_f32_16x16x32_bf16 v[114:117], v[146:149], v[186:189], v[114:117]
	v_mfma_f32_16x16x32_bf16 v[104:107], v[154:157], v[186:189], v[104:107]
	v_mfma_f32_16x16x32_bf16 v[96:99], v[146:149], v[194:197], v[96:99]
	v_mfma_f32_16x16x32_bf16 v[88:91], v[154:157], v[194:197], v[88:91]
	v_mfma_f32_16x16x32_bf16 v[80:83], v[146:149], v[208:211], v[80:83]
	v_mfma_f32_16x16x32_bf16 v[72:75], v[154:157], v[208:211], v[72:75]
	v_mfma_f32_16x16x32_bf16 v[126:129], v[150:153], v[182:185], v[126:129]
	v_mfma_f32_16x16x32_bf16 v[122:125], v[158:161], v[182:185], v[122:125]
	v_mfma_f32_16x16x32_bf16 v[114:117], v[150:153], v[190:193], v[114:117]
	v_mfma_f32_16x16x32_bf16 v[104:107], v[158:161], v[190:193], v[104:107]
	v_mfma_f32_16x16x32_bf16 v[96:99], v[150:153], v[204:207], v[96:99]
	v_mfma_f32_16x16x32_bf16 v[88:91], v[158:161], v[204:207], v[88:91]
	v_mfma_f32_16x16x32_bf16 v[80:83], v[150:153], v[212:215], v[80:83]
	v_mfma_f32_16x16x32_bf16 v[72:75], v[158:161], v[212:215], v[72:75]
	v_mfma_f32_16x16x32_bf16 v[118:121], v[162:165], v[178:181], v[118:121]
	v_mfma_f32_16x16x32_bf16 v[108:111], v[170:173], v[178:181], v[108:111]
	v_mfma_f32_16x16x32_bf16 v[100:103], v[162:165], v[186:189], v[100:103]
	v_mfma_f32_16x16x32_bf16 v[92:95], v[170:173], v[186:189], v[92:95]
	v_mfma_f32_16x16x32_bf16 v[84:87], v[162:165], v[194:197], v[84:87]
	v_mfma_f32_16x16x32_bf16 v[76:79], v[170:173], v[194:197], v[76:79]
	v_mfma_f32_16x16x32_bf16 v[68:71], v[162:165], v[208:211], v[68:71]
	v_mfma_f32_16x16x32_bf16 v[64:67], v[170:173], v[208:211], v[64:67]
	v_mfma_f32_16x16x32_bf16 v[118:121], v[166:169], v[182:185], v[118:121]
	v_mfma_f32_16x16x32_bf16 v[108:111], v[174:177], v[182:185], v[108:111]
	v_mfma_f32_16x16x32_bf16 v[100:103], v[166:169], v[190:193], v[100:103]
	v_mfma_f32_16x16x32_bf16 v[92:95], v[174:177], v[190:193], v[92:95]
	v_mfma_f32_16x16x32_bf16 v[84:87], v[166:169], v[204:207], v[84:87]
	v_mfma_f32_16x16x32_bf16 v[76:79], v[174:177], v[204:207], v[76:79]
	v_mfma_f32_16x16x32_bf16 v[68:71], v[166:169], v[212:215], v[68:71]
	v_mfma_f32_16x16x32_bf16 v[64:67], v[174:177], v[212:215], v[64:67]
	s_barrier
	s_add_i32 s48, s48, s24
	v_lshl_add_u64 v[140:141], s[44:45], 0, v[112:113]
	s_mov_b32 m0, s48
	ds_read_b128 v[178:181], v145 offset:16384
	ds_read_b128 v[182:185], v145 offset:17408
	ds_read_b128 v[186:189], v145 offset:18432
	ds_read_b128 v[190:193], v145 offset:19456
	ds_read_b128 v[194:197], v145 offset:20480
	ds_read_b128 v[204:207], v145 offset:21504
	ds_read_b128 v[208:211], v145 offset:22528
	ds_read_b128 v[212:215], v145 offset:23552
	global_load_lds_dwordx4 v[140:141], off
	s_add_i32 m0, s48, 0x2000
	s_add_u32 s48, s44, 0x80000
	v_lshl_add_u64 v[198:199], s[44:45], 0, v[134:135]
	s_addc_u32 s49, s45, 0
	s_add_i32 s50, s50, s24
	global_load_lds_dwordx4 v[198:199], off
	v_lshl_add_u64 v[216:217], s[48:49], 0, v[112:113]
	s_mov_b32 m0, s50
	v_lshl_add_u64 v[218:219], s[46:47], 0, v[132:133]
	global_load_lds_dwordx4 v[216:217], off
	v_lshl_add_u64 v[216:217], s[48:49], 0, v[134:135]
	s_add_i32 m0, s50, 0x2000
	s_nop 0
	global_load_lds_dwordx4 v[216:217], off
	v_lshl_add_u64 v[216:217], s[46:47], 0, v[130:131]
	s_mov_b32 m0, s25
	s_nop 0
	global_load_lds_dwordx4 v[216:217], off
	s_mov_b32 m0, s27
	s_nop 0
	global_load_lds_dwordx4 v[218:219], off
	s_waitcnt vmcnt(8)
	s_waitcnt lgkmcnt(0)
	s_barrier
; #define PG8_STAGE(bufoff, gbase, voff) do { _Pragma("unroll") for (int _i = 0; _i < 2; ++_i) \
;         __builtin_amdgcn_global_load_lds((const unsigned*)((const char*)(gbase) + (voff)[_i]), (PG8_LAS unsigned*)(lds + (bufoff) + ldsw + _i * 8192), 16, 0, 0); } while (0)
; #define PG8_LDA(dst, b, h) do { if (PG8_MSK && !(mk & (3 << (2 * (h))))) break; _Pragma("unroll") for (int m = 0; m < 4; ++m) _Pragma("unroll") for (int k = 0; k < 2; ++k) dst[m][k] = *(const PG8_LAS bf16x8*)(lds + PG8_SA(b, h) + aoff + m * 2048 + k * 1024); } while (0)
; #define PG8_LDB(dst, b, h) do { if (PG8_MSK && !(mk & (5 << (h)))) break; _Pragma("unroll") for (int n = 0; n < 2; ++n) _Pragma("unroll") for (int k = 0; k < 2; ++k) dst[n][k] = *(const PG8_LAS bf16x8*)(lds + PG8_SB(b, h) + boff + n * 2048 + k * 1024); } while (0)
; #define PG8_WAIT_V(n) asm volatile("s_waitcnt vmcnt(" #n ")" ::: "memory")
; #define PG8_WAIT_L(n) asm volatile("s_waitcnt lgkmcnt(" #n ")" ::: "memory")
; #define PG8_BAR __builtin_amdgcn_s_barrier()
; #define PG8_SCHED __builtin_amdgcn_sched_barrier(0)
; template <class Epi, class Sched, bool ALIGN_EPI = false, bool SP2 = false>
; __device__ __forceinline__ void gemm_phase(PG8_LAS unsigned char* lds, const Gemm g, const Sched& S, const Epi& E, const int tid) {
;     ...
;             PG8_WAIT_V(8); PG8_WAIT_L(0); PG8_BAR; PG8_MMA(0, 0, At, B0); PG8_MMA(0, 1, At, B1); PG8_BAR; PG8_SCHED;
;             PG8_LDA(At, 0, 1); PG8_STAGE(PG8_SB(0, 0), b2, voffB); PG8_STAGE(PG8_SB(0, 1), b2 + hstep, voffB); PG8_STAGE(PG8_SA(0, 0), a2, voffA);
;             PG8_WAIT_V(8); PG8_WAIT_L(0); PG8_BAR; PG8_MMA(1, 0, At, B0); PG8_MMA(1, 1, At, B1); PG8_BAR; PG8_SCHED;
;             PG8_LDB(B0, 1, 0); PG8_LDB(B1, 1, 1); PG8_SCHED; PG8_LDA(At, 1, 0); PG8_STAGE(PG8_SA(0, 1), a2 + hstep, voffA);
;             PG8_WAIT_V(8); PG8_WAIT_L(0); PG8_BAR; PG8_MMA(0, 0, At, B0); PG8_MMA(0, 1, At, B1); PG8_BAR; PG8_SCHED;
	s_waitcnt lgkmcnt(0)
	v_mfma_f32_16x16x32_bf16 v[60:63], v[146:149], v[178:181], v[60:63]
	v_mfma_f32_16x16x32_bf16 v[56:59], v[154:157], v[178:181], v[56:59]
	v_mfma_f32_16x16x32_bf16 v[48:51], v[146:149], v[186:189], v[48:51]
	v_mfma_f32_16x16x32_bf16 v[40:43], v[154:157], v[186:189], v[40:43]
	v_mfma_f32_16x16x32_bf16 v[32:35], v[146:149], v[194:197], v[32:35]
	v_mfma_f32_16x16x32_bf16 v[24:27], v[154:157], v[194:197], v[24:27]
	v_mfma_f32_16x16x32_bf16 v[16:19], v[146:149], v[208:211], v[16:19]
	v_mfma_f32_16x16x32_bf16 v[8:11], v[154:157], v[208:211], v[8:11]
	v_mfma_f32_16x16x32_bf16 v[60:63], v[150:153], v[182:185], v[60:63]
	v_mfma_f32_16x16x32_bf16 v[56:59], v[158:161], v[182:185], v[56:59]
	v_mfma_f32_16x16x32_bf16 v[48:51], v[150:153], v[190:193], v[48:51]
	v_mfma_f32_16x16x32_bf16 v[40:43], v[158:161], v[190:193], v[40:43]
	v_mfma_f32_16x16x32_bf16 v[32:35], v[150:153], v[204:207], v[32:35]
	v_mfma_f32_16x16x32_bf16 v[24:27], v[158:161], v[204:207], v[24:27]
	v_mfma_f32_16x16x32_bf16 v[16:19], v[150:153], v[212:215], v[16:19]
	v_mfma_f32_16x16x32_bf16 v[8:11], v[158:161], v[212:215], v[8:11]
	v_mfma_f32_16x16x32_bf16 v[52:55], v[162:165], v[178:181], v[52:55]
	v_mfma_f32_16x16x32_bf16 v[44:47], v[170:173], v[178:181], v[44:47]
	v_mfma_f32_16x16x32_bf16 v[36:39], v[162:165], v[186:189], v[36:39]
	v_mfma_f32_16x16x32_bf16 v[28:31], v[170:173], v[186:189], v[28:31]
	v_mfma_f32_16x16x32_bf16 v[20:23], v[162:165], v[194:197], v[20:23]
	v_mfma_f32_16x16x32_bf16 v[12:15], v[170:173], v[194:197], v[12:15]
	v_mfma_f32_16x16x32_bf16 v[4:7], v[162:165], v[208:211], v[4:7]
	v_mfma_f32_16x16x32_bf16 v[0:3], v[170:173], v[208:211], v[0:3]
	v_mfma_f32_16x16x32_bf16 v[52:55], v[166:169], v[182:185], v[52:55]
	v_mfma_f32_16x16x32_bf16 v[44:47], v[174:177], v[182:185], v[44:47]
	v_mfma_f32_16x16x32_bf16 v[36:39], v[166:169], v[190:193], v[36:39]
	v_mfma_f32_16x16x32_bf16 v[28:31], v[174:177], v[190:193], v[28:31]
	v_mfma_f32_16x16x32_bf16 v[20:23], v[166:169], v[204:207], v[20:23]
	v_mfma_f32_16x16x32_bf16 v[12:15], v[174:177], v[204:207], v[12:15]
	v_mfma_f32_16x16x32_bf16 v[4:7], v[166:169], v[212:215], v[4:7]
	v_mfma_f32_16x16x32_bf16 v[0:3], v[174:177], v[212:215], v[0:3]
	s_barrier
	s_add_i32 s48, 0, 0x18000
	s_add_i32 s49, 0, 0x1c000
	v_add_u32_e32 v158, s48, v143
	v_add_u32_e32 v174, s49, v143
	ds_read_b128 v[146:149], v158
	ds_read_b128 v[150:153], v158 offset:1024
	ds_read_b128 v[154:157], v158 offset:2048
	ds_read_b128 v[158:161], v158 offset:3072
	ds_read_b128 v[162:165], v174
	ds_read_b128 v[166:169], v174 offset:1024
	ds_read_b128 v[170:173], v174 offset:2048
	ds_read_b128 v[174:177], v174 offset:3072
	s_add_u32 s46, s46, 0x80000
	s_addc_u32 s47, s47, 0
	s_mov_b32 m0, s33
	v_lshl_add_u64 v[220:221], s[46:47], 0, v[130:131]
	ds_read_b128 v[178:181], v145 offset:32768
	ds_read_b128 v[182:185], v145 offset:33792
	ds_read_b128 v[186:189], v145 offset:34816
	ds_read_b128 v[190:193], v145 offset:35840
	ds_read_b128 v[194:197], v145 offset:36864
	ds_read_b128 v[204:207], v145 offset:37888
	ds_read_b128 v[208:211], v145 offset:38912
	ds_read_b128 v[212:215], v145 offset:39936
	global_load_lds_dwordx4 v[220:221], off
	v_lshl_add_u64 v[220:221], s[46:47], 0, v[132:133]
	s_mov_b32 m0, s36
	s_nop 0
	global_load_lds_dwordx4 v[220:221], off
	s_waitcnt vmcnt(8)
	s_waitcnt lgkmcnt(0)
	s_barrier
	s_waitcnt lgkmcnt(0)
	v_mfma_f32_16x16x32_bf16 v[126:129], v[146:149], v[178:181], v[126:129]
	v_mfma_f32_16x16x32_bf16 v[122:125], v[154:157], v[178:181], v[122:125]
	v_mfma_f32_16x16x32_bf16 v[114:117], v[146:149], v[186:189], v[114:117]
	v_mfma_f32_16x16x32_bf16 v[104:107], v[154:157], v[186:189], v[104:107]
	v_mfma_f32_16x16x32_bf16 v[96:99], v[146:149], v[194:197], v[96:99]
	v_mfma_f32_16x16x32_bf16 v[88:91], v[154:157], v[194:197], v[88:91]
	v_mfma_f32_16x16x32_bf16 v[80:83], v[146:149], v[208:211], v[80:83]
	v_mfma_f32_16x16x32_bf16 v[72:75], v[154:157], v[208:211], v[72:75]
	v_mfma_f32_16x16x32_bf16 v[126:129], v[150:153], v[182:185], v[126:129]
	v_mfma_f32_16x16x32_bf16 v[122:125], v[158:161], v[182:185], v[122:125]
	v_mfma_f32_16x16x32_bf16 v[114:117], v[150:153], v[190:193], v[114:117]
	v_mfma_f32_16x16x32_bf16 v[104:107], v[158:161], v[190:193], v[104:107]
	v_mfma_f32_16x16x32_bf16 v[96:99], v[150:153], v[204:207], v[96:99]
	v_mfma_f32_16x16x32_bf16 v[88:91], v[158:161], v[204:207], v[88:91]
	v_mfma_f32_16x16x32_bf16 v[80:83], v[150:153], v[212:215], v[80:83]
	v_mfma_f32_16x16x32_bf16 v[72:75], v[158:161], v[212:215], v[72:75]
	v_mfma_f32_16x16x32_bf16 v[118:121], v[162:165], v[178:181], v[118:121]
	v_mfma_f32_16x16x32_bf16 v[108:111], v[170:173], v[178:181], v[108:111]
	v_mfma_f32_16x16x32_bf16 v[100:103], v[162:165], v[186:189], v[100:103]
	v_mfma_f32_16x16x32_bf16 v[92:95], v[170:173], v[186:189], v[92:95]
	v_mfma_f32_16x16x32_bf16 v[84:87], v[162:165], v[194:197], v[84:87]
	v_mfma_f32_16x16x32_bf16 v[76:79], v[170:173], v[194:197], v[76:79]
	v_mfma_f32_16x16x32_bf16 v[68:71], v[162:165], v[208:211], v[68:71]
	v_mfma_f32_16x16x32_bf16 v[64:67], v[170:173], v[208:211], v[64:67]
	v_mfma_f32_16x16x32_bf16 v[118:121], v[166:169], v[182:185], v[118:121]
	v_mfma_f32_16x16x32_bf16 v[108:111], v[174:177], v[182:185], v[108:111]
	v_mfma_f32_16x16x32_bf16 v[100:103], v[166:169], v[190:193], v[100:103]
	v_mfma_f32_16x16x32_bf16 v[92:95], v[174:177], v[190:193], v[92:95]
	v_mfma_f32_16x16x32_bf16 v[84:87], v[166:169], v[204:207], v[84:87]
	v_mfma_f32_16x16x32_bf16 v[76:79], v[174:177], v[204:207], v[76:79]
	v_mfma_f32_16x16x32_bf16 v[68:71], v[166:169], v[212:215], v[68:71]
	v_mfma_f32_16x16x32_bf16 v[64:67], v[174:177], v[212:215], v[64:67]
	s_barrier
; #define PG8_STAGE(bufoff, gbase, voff) do { _Pragma("unroll") for (int _i = 0; _i < 2; ++_i) \
;         __builtin_amdgcn_global_load_lds((const unsigned*)((const char*)(gbase) + (voff)[_i]), (PG8_LAS unsigned*)(lds + (bufoff) + ldsw + _i * 8192), 16, 0, 0); } while (0)
; #define PG8_LDA(dst, b, h) do { if (PG8_MSK && !(mk & (3 << (2 * (h))))) break; _Pragma("unroll") for (int m = 0; m < 4; ++m) _Pragma("unroll") for (int k = 0; k < 2; ++k) dst[m][k] = *(const PG8_LAS bf16x8*)(lds + PG8_SA(b, h) + aoff + m * 2048 + k * 1024); } while (0)
; #define PG8_WAIT_V(n) asm volatile("s_waitcnt vmcnt(" #n ")" ::: "memory")
; #define PG8_WAIT_L(n) asm volatile("s_waitcnt lgkmcnt(" #n ")" ::: "memory")
; #define PG8_BAR __builtin_amdgcn_s_barrier()
; #define PG8_SCHED __builtin_amdgcn_sched_barrier(0)
; template <class Epi, class Sched, bool ALIGN_EPI = false, bool SP2 = false>
; __device__ __forceinline__ void gemm_phase(PG8_LAS unsigned char* lds, const Gemm g, const Sched& S, const Epi& E, const int tid) {
;     ...
;         for (int t = 0; t < nt; t += 2) {
;             const bool last = (t == nt - 2);
;             if constexpr (Epi::MID) { if (E.use_rs && t == (nt >> 1)) E.mid(acc, cur, wr, fr); }
;             const char* a1 = cA + (size_t)(t + 1) * kstep;
;             const char* a2 = last ? nA : cA + (size_t)(t + 2) * kstep; const char* b2 = last ? nB : cB + (size_t)(t + 2) * kstep;
;     ...
;             PG8_LDA(At, 1, 1); PG8_STAGE(PG8_SB(1, 0), b3, voffB); PG8_STAGE(PG8_SB(1, 1), b3 + hstep, voffB); PG8_STAGE(PG8_SA(1, 0), a3, voffA);
;             PG8_WAIT_V(8); PG8_WAIT_L(0); PG8_BAR; PG8_MMA(1, 0, At, B0); PG8_MMA(1, 1, At, B1); PG8_BAR; PG8_SCHED;
	s_add_i32 s46, s48, s24
	v_lshl_add_u64 v[140:141], v[140:141], 0, s[34:35]
	s_mov_b32 m0, s46
	ds_read_b128 v[178:181], v145 offset:49152
	ds_read_b128 v[182:185], v145 offset:50176
	ds_read_b128 v[186:189], v145 offset:51200
	ds_read_b128 v[190:193], v145 offset:52224
	ds_read_b128 v[194:197], v145 offset:53248
	ds_read_b128 v[204:207], v145 offset:54272
	ds_read_b128 v[208:211], v145 offset:55296
	ds_read_b128 v[212:215], v145 offset:56320
	global_load_lds_dwordx4 v[140:141], off
	s_add_i32 m0, s46, 0x2000
	s_add_u32 s44, s44, 0x80080
	v_lshl_add_u64 v[140:141], v[198:199], 0, s[34:35]
	s_addc_u32 s45, s45, 0
	s_add_i32 s46, s49, s24
	global_load_lds_dwordx4 v[140:141], off
	v_lshl_add_u64 v[140:141], s[44:45], 0, v[112:113]
	s_mov_b32 m0, s46
	s_nop 0
	global_load_lds_dwordx4 v[140:141], off
	v_lshl_add_u64 v[140:141], s[44:45], 0, v[134:135]
	s_add_i32 m0, s46, 0x2000
	s_nop 0
	global_load_lds_dwordx4 v[140:141], off
	v_lshl_add_u64 v[140:141], v[216:217], 0, s[34:35]
	s_mov_b32 m0, s30
	s_nop 0
	global_load_lds_dwordx4 v[140:141], off
	v_lshl_add_u64 v[140:141], v[218:219], 0, s[34:35]
	s_mov_b32 m0, s37
	s_nop 0
	global_load_lds_dwordx4 v[140:141], off
	s_waitcnt vmcnt(8)
	s_waitcnt lgkmcnt(0)
	s_barrier
	s_waitcnt lgkmcnt(0)
	v_mfma_f32_16x16x32_bf16 v[60:63], v[146:149], v[178:181], v[60:63]
	v_mfma_f32_16x16x32_bf16 v[56:59], v[154:157], v[178:181], v[56:59]
	v_mfma_f32_16x16x32_bf16 v[48:51], v[146:149], v[186:189], v[48:51]
	v_mfma_f32_16x16x32_bf16 v[40:43], v[154:157], v[186:189], v[40:43]
	v_mfma_f32_16x16x32_bf16 v[32:35], v[146:149], v[194:197], v[32:35]
	v_mfma_f32_16x16x32_bf16 v[24:27], v[154:157], v[194:197], v[24:27]
	v_mfma_f32_16x16x32_bf16 v[16:19], v[146:149], v[208:211], v[16:19]
	v_mfma_f32_16x16x32_bf16 v[8:11], v[154:157], v[208:211], v[8:11]
	v_mfma_f32_16x16x32_bf16 v[60:63], v[150:153], v[182:185], v[60:63]
	v_mfma_f32_16x16x32_bf16 v[56:59], v[158:161], v[182:185], v[56:59]
	v_mfma_f32_16x16x32_bf16 v[48:51], v[150:153], v[190:193], v[48:51]
	v_mfma_f32_16x16x32_bf16 v[40:43], v[158:161], v[190:193], v[40:43]
	v_mfma_f32_16x16x32_bf16 v[32:35], v[150:153], v[204:207], v[32:35]
	v_mfma_f32_16x16x32_bf16 v[24:27], v[158:161], v[204:207], v[24:27]
	v_mfma_f32_16x16x32_bf16 v[16:19], v[150:153], v[212:215], v[16:19]
	v_mfma_f32_16x16x32_bf16 v[8:11], v[158:161], v[212:215], v[8:11]
	v_mfma_f32_16x16x32_bf16 v[52:55], v[162:165], v[178:181], v[52:55]
	v_mfma_f32_16x16x32_bf16 v[44:47], v[170:173], v[178:181], v[44:47]
	v_mfma_f32_16x16x32_bf16 v[36:39], v[162:165], v[186:189], v[36:39]
	v_mfma_f32_16x16x32_bf16 v[28:31], v[170:173], v[186:189], v[28:31]
	v_mfma_f32_16x16x32_bf16 v[20:23], v[162:165], v[194:197], v[20:23]
	v_mfma_f32_16x16x32_bf16 v[12:15], v[170:173], v[194:197], v[12:15]
	v_mfma_f32_16x16x32_bf16 v[4:7], v[162:165], v[208:211], v[4:7]
	v_mfma_f32_16x16x32_bf16 v[0:3], v[170:173], v[208:211], v[0:3]
	v_mfma_f32_16x16x32_bf16 v[52:55], v[166:169], v[182:185], v[52:55]
	v_mfma_f32_16x16x32_bf16 v[44:47], v[174:177], v[182:185], v[44:47]
	v_mfma_f32_16x16x32_bf16 v[36:39], v[166:169], v[190:193], v[36:39]
	v_mfma_f32_16x16x32_bf16 v[28:31], v[174:177], v[190:193], v[28:31]
	v_mfma_f32_16x16x32_bf16 v[20:23], v[166:169], v[204:207], v[20:23]
	v_mfma_f32_16x16x32_bf16 v[12:15], v[174:177], v[204:207], v[12:15]
	v_mfma_f32_16x16x32_bf16 v[4:7], v[166:169], v[212:215], v[4:7]
	v_mfma_f32_16x16x32_bf16 v[0:3], v[174:177], v[212:215], v[0:3]
	s_barrier
	s_add_i32 s41, s41, 2
	s_add_u32 s42, s42, 0x100
	s_addc_u32 s43, s43, 0
	s_add_u32 s15, s15, 0x100
	s_addc_u32 s39, s39, 0
	s_cmp_lt_u32 s41, 30
	s_cbranch_scc1 .LBB0_338
	s_andn2_b64 vcc, exec, s[8:9]
	s_mov_b32 s39, 0x7e000
	v_readlane_b32 s13, v254, 24
	s_cbranch_vccnz .LBB0_341
	s_barrier

; #define PG8_STAGE(bufoff, gbase, voff) do { _Pragma("unroll") for (int _i = 0; _i < 2; ++_i) \
;         __builtin_amdgcn_global_load_lds((const unsigned*)((const char*)(gbase) + (voff)[_i]), (PG8_LAS unsigned*)(lds + (bufoff) + ldsw + _i * 8192), 16, 0, 0); } while (0)
; #define PG8_LDA(dst, b, h) do { if (PG8_MSK && !(mk & (3 << (2 * (h))))) break; _Pragma("unroll") for (int m = 0; m < 4; ++m) _Pragma("unroll") for (int k = 0; k < 2; ++k) dst[m][k] = *(const PG8_LAS bf16x8*)(lds + PG8_SA(b, h) + aoff + m * 2048 + k * 1024); } while (0)
; #define PG8_BAR __builtin_amdgcn_s_barrier()
; template <class Epi, class Sched, bool ALIGN_EPI = false, bool SP2 = false>
; __device__ __forceinline__ void gemm_phase(PG8_LAS unsigned char* lds, const Gemm g, const Sched& S, const Epi& E, const int tid) {
;     ...
;         for (int t = 0; t < nt; t += 2) {
;             const bool last = (t == nt - 2);
;             if constexpr (Epi::MID) { if (E.use_rs && t == (nt >> 1)) E.mid(acc, cur, wr, fr); }
;             const char* a1 = cA + (size_t)(t + 1) * kstep;
;             const char* a2 = last ? nA : cA + (size_t)(t + 2) * kstep; const char* b2 = last ? nB : cB + (size_t)(t + 2) * kstep;
;             const char* a3 = a2 + kstep; const char* b3 = b2 + kstep;
;             if (last && has_next) S.a_ready(nxt);
;             if constexpr (SP2) {
;             PG8_LDB(B0, 0, 0); PG8_LDB(B1, 0, 1); PG8_SCHED; PG8_LDA(At, 0, 0); PG8_STAGE(PG8_SA(1, 1), a1 + hstep, voffA);
;             PG8_WAIT_V(8); PG8_WAIT_L(0); PG8_BAR; PG8_MMA(0, 0, At, B0); PG8_MMA(0, 1, At, B1); PG8_BAR; PG8_SCHED;
;             PG8_LDA(At, 0, 1); PG8_STAGE(PG8_SB(0, 0), b2, voffB); PG8_STAGE(PG8_SB(0, 1), b2 + hstep, voffB); PG8_STAGE(PG8_SA(0, 0), a2, voffA);
;             PG8_WAIT_V(8); PG8_WAIT_L(0); PG8_BAR; PG8_MMA(1, 0, At, B0); PG8_MMA(1, 1, At, B1); PG8_BAR; PG8_SCHED;
;             PG8_LDB(B0, 1, 0); PG8_LDB(B1, 1, 1); PG8_SCHED; PG8_LDA(At, 1, 0); PG8_STAGE(PG8_SA(0, 1), a2 + hstep, voffA);
;             PG8_WAIT_V(8); PG8_WAIT_L(0); PG8_BAR; PG8_MMA(0, 0, At, B0); PG8_MMA(0, 1, At, B1); PG8_BAR; PG8_SCHED;
;             PG8_LDA(At, 1, 1); PG8_STAGE(PG8_SB(1, 0), b3, voffB); PG8_STAGE(PG8_SB(1, 1), b3 + hstep, voffB); PG8_STAGE(PG8_SA(1, 0), a3, voffA);
;             PG8_WAIT_V(8); PG8_WAIT_L(0); PG8_BAR; PG8_MMA(1, 0, At, B0); PG8_MMA(1, 1, At, B1); PG8_BAR; PG8_SCHED;
.LBB0_424:
	s_add_i32 s64, s48, 2
	s_add_u32 s65, s28, s46
	s_addc_u32 s49, s29, s47
	s_add_u32 s66, s22, s46
	s_addc_u32 s67, s23, s47
	s_add_i32 s68, 0, 0x10000
	s_cmp_eq_u32 s58, s48
	s_cselect_b32 s49, s9, s49
	s_cselect_b32 s48, s8, s65
	v_add_u32_e32 v112, s68, v146
	s_cselect_b32 s67, s45, s67
	s_cselect_b32 s66, s44, s66
	s_add_i32 s65, 0, 0x14000
	ds_read_b128 v[148:151], v112
	ds_read_b128 v[152:155], v112 offset:1024
	ds_read_b128 v[156:159], v112 offset:2048
	ds_read_b128 v[160:163], v112 offset:3072
	v_add_u32_e32 v112, s65, v146
	ds_read_b128 v[164:167], v112
	ds_read_b128 v[168:171], v112 offset:1024
	ds_read_b128 v[172:175], v112 offset:2048
	ds_read_b128 v[176:179], v112 offset:3072
	v_lshl_add_u64 v[218:219], s[28:29], 0, v[144:145]
	s_add_i32 m0, s50, 0xc000
	ds_read_b128 v[180:183], v147
	ds_read_b128 v[184:187], v147 offset:1024
	ds_read_b128 v[188:191], v147 offset:2048
	ds_read_b128 v[192:195], v147 offset:3072
	ds_read_b128 v[196:199], v147 offset:4096
	ds_read_b128 v[204:207], v147 offset:5120
	ds_read_b128 v[208:211], v147 offset:6144
	ds_read_b128 v[212:215], v147 offset:7168
	global_load_lds_dwordx4 v[218:219], off
	v_lshl_add_u64 v[218:219], s[28:29], 0, v[114:115]
	s_add_i32 m0, s50, 0xe000
	s_nop 0
	global_load_lds_dwordx4 v[218:219], off
	s_waitcnt vmcnt(8)
	s_waitcnt lgkmcnt(0)
	s_barrier
	s_waitcnt lgkmcnt(0)
	v_mfma_f32_16x16x32_bf16 v[128:131], v[148:151], v[180:183], v[128:131]
	v_mfma_f32_16x16x32_bf16 v[124:127], v[156:159], v[180:183], v[124:127]
	v_mfma_f32_16x16x32_bf16 v[108:111], v[148:151], v[188:191], v[108:111]
	v_mfma_f32_16x16x32_bf16 v[104:107], v[156:159], v[188:191], v[104:107]
	v_mfma_f32_16x16x32_bf16 v[92:95], v[148:151], v[196:199], v[92:95]
	v_mfma_f32_16x16x32_bf16 v[88:91], v[156:159], v[196:199], v[88:91]
	v_mfma_f32_16x16x32_bf16 v[76:79], v[148:151], v[208:211], v[76:79]
	v_mfma_f32_16x16x32_bf16 v[72:75], v[156:159], v[208:211], v[72:75]
	v_mfma_f32_16x16x32_bf16 v[128:131], v[152:155], v[184:187], v[128:131]
	v_mfma_f32_16x16x32_bf16 v[124:127], v[160:163], v[184:187], v[124:127]
	v_mfma_f32_16x16x32_bf16 v[108:111], v[152:155], v[192:195], v[108:111]
	v_mfma_f32_16x16x32_bf16 v[104:107], v[160:163], v[192:195], v[104:107]
	v_mfma_f32_16x16x32_bf16 v[92:95], v[152:155], v[204:207], v[92:95]
	v_mfma_f32_16x16x32_bf16 v[88:91], v[160:163], v[204:207], v[88:91]
	v_mfma_f32_16x16x32_bf16 v[76:79], v[152:155], v[212:215], v[76:79]
	v_mfma_f32_16x16x32_bf16 v[72:75], v[160:163], v[212:215], v[72:75]
	v_mfma_f32_16x16x32_bf16 v[120:123], v[164:167], v[180:183], v[120:123]
	v_mfma_f32_16x16x32_bf16 v[116:119], v[172:175], v[180:183], v[116:119]
	v_mfma_f32_16x16x32_bf16 v[100:103], v[164:167], v[188:191], v[100:103]
	v_mfma_f32_16x16x32_bf16 v[96:99], v[172:175], v[188:191], v[96:99]
	v_mfma_f32_16x16x32_bf16 v[84:87], v[164:167], v[196:199], v[84:87]
	v_mfma_f32_16x16x32_bf16 v[80:83], v[172:175], v[196:199], v[80:83]
	v_mfma_f32_16x16x32_bf16 v[68:71], v[164:167], v[208:211], v[68:71]
	v_mfma_f32_16x16x32_bf16 v[64:67], v[172:175], v[208:211], v[64:67]
	v_mfma_f32_16x16x32_bf16 v[120:123], v[168:171], v[184:187], v[120:123]
	v_mfma_f32_16x16x32_bf16 v[116:119], v[176:179], v[184:187], v[116:119]
	v_mfma_f32_16x16x32_bf16 v[100:103], v[168:171], v[192:195], v[100:103]
	v_mfma_f32_16x16x32_bf16 v[96:99], v[176:179], v[192:195], v[96:99]
	v_mfma_f32_16x16x32_bf16 v[84:87], v[168:171], v[204:207], v[84:87]
	v_mfma_f32_16x16x32_bf16 v[80:83], v[176:179], v[204:207], v[80:83]
	v_mfma_f32_16x16x32_bf16 v[68:71], v[168:171], v[212:215], v[68:71]
	v_mfma_f32_16x16x32_bf16 v[64:67], v[176:179], v[212:215], v[64:67]
	s_barrier
	s_add_i32 s68, s68, s33
	v_lshl_add_u64 v[218:219], s[66:67], 0, v[136:137]
	s_mov_b32 m0, s68
	ds_read_b128 v[180:183], v147 offset:16384
	ds_read_b128 v[184:187], v147 offset:17408
	ds_read_b128 v[188:191], v147 offset:18432
	ds_read_b128 v[192:195], v147 offset:19456
	ds_read_b128 v[196:199], v147 offset:20480
	ds_read_b128 v[204:207], v147 offset:21504
	ds_read_b128 v[208:211], v147 offset:22528
	ds_read_b128 v[212:215], v147 offset:23552
	global_load_lds_dwordx4 v[218:219], off
	s_add_i32 m0, s68, 0x2000
	v_lshl_add_u64 v[220:221], s[66:67], 0, v[132:133]
	s_add_u32 s66, s66, s17
	s_addc_u32 s67, s67, 0
	s_add_i32 s65, s65, s33
	global_load_lds_dwordx4 v[220:221], off
	v_lshl_add_u64 v[222:223], s[66:67], 0, v[136:137]
	s_mov_b32 m0, s65
	v_lshl_add_u64 v[224:225], s[66:67], 0, v[132:133]
	global_load_lds_dwordx4 v[222:223], off
	s_add_i32 m0, s65, 0x2000
	v_lshl_add_u64 v[226:227], s[48:49], 0, v[138:139]
	global_load_lds_dwordx4 v[224:225], off
	s_mov_b32 m0, s50
	v_lshl_add_u64 v[228:229], s[48:49], 0, v[134:135]
	global_load_lds_dwordx4 v[226:227], off
	s_mov_b32 m0, s51
	s_nop 0
	global_load_lds_dwordx4 v[228:229], off
	s_waitcnt vmcnt(8)
	s_waitcnt lgkmcnt(0)
	s_barrier
; #define PG8_STAGE(bufoff, gbase, voff) do { _Pragma("unroll") for (int _i = 0; _i < 2; ++_i) \
;         __builtin_amdgcn_global_load_lds((const unsigned*)((const char*)(gbase) + (voff)[_i]), (PG8_LAS unsigned*)(lds + (bufoff) + ldsw + _i * 8192), 16, 0, 0); } while (0)
; #define PG8_LDA(dst, b, h) do { if (PG8_MSK && !(mk & (3 << (2 * (h))))) break; _Pragma("unroll") for (int m = 0; m < 4; ++m) _Pragma("unroll") for (int k = 0; k < 2; ++k) dst[m][k] = *(const PG8_LAS bf16x8*)(lds + PG8_SA(b, h) + aoff + m * 2048 + k * 1024); } while (0)
; #define PG8_LDB(dst, b, h) do { if (PG8_MSK && !(mk & (5 << (h)))) break; _Pragma("unroll") for (int n = 0; n < 2; ++n) _Pragma("unroll") for (int k = 0; k < 2; ++k) dst[n][k] = *(const PG8_LAS bf16x8*)(lds + PG8_SB(b, h) + boff + n * 2048 + k * 1024); } while (0)
; #define PG8_WAIT_V(n) asm volatile("s_waitcnt vmcnt(" #n ")" ::: "memory")
; #define PG8_WAIT_L(n) asm volatile("s_waitcnt lgkmcnt(" #n ")" ::: "memory")
; #define PG8_BAR __builtin_amdgcn_s_barrier()
; #define PG8_SCHED __builtin_amdgcn_sched_barrier(0)
; template <class Epi, class Sched, bool ALIGN_EPI = false, bool SP2 = false>
; __device__ __forceinline__ void gemm_phase(PG8_LAS unsigned char* lds, const Gemm g, const Sched& S, const Epi& E, const int tid) {
;     ...
;             PG8_WAIT_V(8); PG8_WAIT_L(0); PG8_BAR; PG8_MMA(0, 0, At, B0); PG8_MMA(0, 1, At, B1); PG8_BAR; PG8_SCHED;
;             PG8_LDA(At, 0, 1); PG8_STAGE(PG8_SB(0, 0), b2, voffB); PG8_STAGE(PG8_SB(0, 1), b2 + hstep, voffB); PG8_STAGE(PG8_SA(0, 0), a2, voffA);
;             PG8_WAIT_V(8); PG8_WAIT_L(0); PG8_BAR; PG8_MMA(1, 0, At, B0); PG8_MMA(1, 1, At, B1); PG8_BAR; PG8_SCHED;
;             PG8_LDB(B0, 1, 0); PG8_LDB(B1, 1, 1); PG8_SCHED; PG8_LDA(At, 1, 0); PG8_STAGE(PG8_SA(0, 1), a2 + hstep, voffA);
;             PG8_WAIT_V(8); PG8_WAIT_L(0); PG8_BAR; PG8_MMA(0, 0, At, B0); PG8_MMA(0, 1, At, B1); PG8_BAR; PG8_SCHED;
	s_waitcnt lgkmcnt(0)
	v_mfma_f32_16x16x32_bf16 v[60:63], v[148:151], v[180:183], v[60:63]
	v_mfma_f32_16x16x32_bf16 v[56:59], v[156:159], v[180:183], v[56:59]
	v_mfma_f32_16x16x32_bf16 v[44:47], v[148:151], v[188:191], v[44:47]
	v_mfma_f32_16x16x32_bf16 v[40:43], v[156:159], v[188:191], v[40:43]
	v_mfma_f32_16x16x32_bf16 v[28:31], v[148:151], v[196:199], v[28:31]
	v_mfma_f32_16x16x32_bf16 v[24:27], v[156:159], v[196:199], v[24:27]
	v_mfma_f32_16x16x32_bf16 v[12:15], v[148:151], v[208:211], v[12:15]
	v_mfma_f32_16x16x32_bf16 v[8:11], v[156:159], v[208:211], v[8:11]
	v_mfma_f32_16x16x32_bf16 v[60:63], v[152:155], v[184:187], v[60:63]
	v_mfma_f32_16x16x32_bf16 v[56:59], v[160:163], v[184:187], v[56:59]
	v_mfma_f32_16x16x32_bf16 v[44:47], v[152:155], v[192:195], v[44:47]
	v_mfma_f32_16x16x32_bf16 v[40:43], v[160:163], v[192:195], v[40:43]
	v_mfma_f32_16x16x32_bf16 v[28:31], v[152:155], v[204:207], v[28:31]
	v_mfma_f32_16x16x32_bf16 v[24:27], v[160:163], v[204:207], v[24:27]
	v_mfma_f32_16x16x32_bf16 v[12:15], v[152:155], v[212:215], v[12:15]
	v_mfma_f32_16x16x32_bf16 v[8:11], v[160:163], v[212:215], v[8:11]
	v_mfma_f32_16x16x32_bf16 v[52:55], v[164:167], v[180:183], v[52:55]
	v_mfma_f32_16x16x32_bf16 v[48:51], v[172:175], v[180:183], v[48:51]
	v_mfma_f32_16x16x32_bf16 v[36:39], v[164:167], v[188:191], v[36:39]
	v_mfma_f32_16x16x32_bf16 v[32:35], v[172:175], v[188:191], v[32:35]
	v_mfma_f32_16x16x32_bf16 v[20:23], v[164:167], v[196:199], v[20:23]
	v_mfma_f32_16x16x32_bf16 v[16:19], v[172:175], v[196:199], v[16:19]
	v_mfma_f32_16x16x32_bf16 v[4:7], v[164:167], v[208:211], v[4:7]
	v_mfma_f32_16x16x32_bf16 v[0:3], v[172:175], v[208:211], v[0:3]
	v_mfma_f32_16x16x32_bf16 v[52:55], v[168:171], v[184:187], v[52:55]
	v_mfma_f32_16x16x32_bf16 v[48:51], v[176:179], v[184:187], v[48:51]
	v_mfma_f32_16x16x32_bf16 v[36:39], v[168:171], v[192:195], v[36:39]
	v_mfma_f32_16x16x32_bf16 v[32:35], v[176:179], v[192:195], v[32:35]
	v_mfma_f32_16x16x32_bf16 v[20:23], v[168:171], v[204:207], v[20:23]
	v_mfma_f32_16x16x32_bf16 v[16:19], v[176:179], v[204:207], v[16:19]
	v_mfma_f32_16x16x32_bf16 v[4:7], v[168:171], v[212:215], v[4:7]
	v_mfma_f32_16x16x32_bf16 v[0:3], v[176:179], v[212:215], v[0:3]
	s_barrier
	s_add_i32 s65, 0, 0x18000
	v_add_u32_e32 v112, s65, v146
	s_add_i32 s66, 0, 0x1c000
	ds_read_b128 v[148:151], v112
	ds_read_b128 v[152:155], v112 offset:1024
	ds_read_b128 v[156:159], v112 offset:2048
	ds_read_b128 v[160:163], v112 offset:3072
	v_add_u32_e32 v112, s66, v146
	ds_read_b128 v[164:167], v112
	ds_read_b128 v[168:171], v112 offset:1024
	ds_read_b128 v[172:175], v112 offset:2048
	ds_read_b128 v[176:179], v112 offset:3072
	s_add_u32 s48, s48, s17
	s_addc_u32 s49, s49, 0
	s_mov_b32 m0, s53
	v_lshl_add_u64 v[234:235], s[48:49], 0, v[138:139]
	ds_read_b128 v[180:183], v147 offset:32768
	ds_read_b128 v[184:187], v147 offset:33792
	ds_read_b128 v[188:191], v147 offset:34816
	ds_read_b128 v[192:195], v147 offset:35840
	ds_read_b128 v[196:199], v147 offset:36864
	ds_read_b128 v[204:207], v147 offset:37888
	ds_read_b128 v[208:211], v147 offset:38912
	ds_read_b128 v[212:215], v147 offset:39936
	global_load_lds_dwordx4 v[234:235], off
	v_lshl_add_u64 v[234:235], s[48:49], 0, v[134:135]
	s_mov_b32 m0, s54
	s_nop 0
	global_load_lds_dwordx4 v[234:235], off
	s_waitcnt vmcnt(8)
	s_waitcnt lgkmcnt(0)
	s_barrier
	s_waitcnt lgkmcnt(0)
	v_mfma_f32_16x16x32_bf16 v[128:131], v[148:151], v[180:183], v[128:131]
	v_mfma_f32_16x16x32_bf16 v[124:127], v[156:159], v[180:183], v[124:127]
	v_mfma_f32_16x16x32_bf16 v[108:111], v[148:151], v[188:191], v[108:111]
	v_mfma_f32_16x16x32_bf16 v[104:107], v[156:159], v[188:191], v[104:107]
	v_mfma_f32_16x16x32_bf16 v[92:95], v[148:151], v[196:199], v[92:95]
	v_mfma_f32_16x16x32_bf16 v[88:91], v[156:159], v[196:199], v[88:91]
	v_mfma_f32_16x16x32_bf16 v[76:79], v[148:151], v[208:211], v[76:79]
	v_mfma_f32_16x16x32_bf16 v[72:75], v[156:159], v[208:211], v[72:75]
	v_mfma_f32_16x16x32_bf16 v[128:131], v[152:155], v[184:187], v[128:131]
	v_mfma_f32_16x16x32_bf16 v[124:127], v[160:163], v[184:187], v[124:127]
	v_mfma_f32_16x16x32_bf16 v[108:111], v[152:155], v[192:195], v[108:111]
	v_mfma_f32_16x16x32_bf16 v[104:107], v[160:163], v[192:195], v[104:107]
	v_mfma_f32_16x16x32_bf16 v[92:95], v[152:155], v[204:207], v[92:95]
	v_mfma_f32_16x16x32_bf16 v[88:91], v[160:163], v[204:207], v[88:91]
	v_mfma_f32_16x16x32_bf16 v[76:79], v[152:155], v[212:215], v[76:79]
	v_mfma_f32_16x16x32_bf16 v[72:75], v[160:163], v[212:215], v[72:75]
	v_mfma_f32_16x16x32_bf16 v[120:123], v[164:167], v[180:183], v[120:123]
	v_mfma_f32_16x16x32_bf16 v[116:119], v[172:175], v[180:183], v[116:119]
	v_mfma_f32_16x16x32_bf16 v[100:103], v[164:167], v[188:191], v[100:103]
	v_mfma_f32_16x16x32_bf16 v[96:99], v[172:175], v[188:191], v[96:99]
	v_mfma_f32_16x16x32_bf16 v[84:87], v[164:167], v[196:199], v[84:87]
	v_mfma_f32_16x16x32_bf16 v[80:83], v[172:175], v[196:199], v[80:83]
	v_mfma_f32_16x16x32_bf16 v[68:71], v[164:167], v[208:211], v[68:71]
	v_mfma_f32_16x16x32_bf16 v[64:67], v[172:175], v[208:211], v[64:67]
	v_mfma_f32_16x16x32_bf16 v[120:123], v[168:171], v[184:187], v[120:123]
	v_mfma_f32_16x16x32_bf16 v[116:119], v[176:179], v[184:187], v[116:119]
	v_mfma_f32_16x16x32_bf16 v[100:103], v[168:171], v[192:195], v[100:103]
	v_mfma_f32_16x16x32_bf16 v[96:99], v[176:179], v[192:195], v[96:99]
	v_mfma_f32_16x16x32_bf16 v[84:87], v[168:171], v[204:207], v[84:87]
	v_mfma_f32_16x16x32_bf16 v[80:83], v[176:179], v[204:207], v[80:83]
	v_mfma_f32_16x16x32_bf16 v[68:71], v[168:171], v[212:215], v[68:71]
	v_mfma_f32_16x16x32_bf16 v[64:67], v[176:179], v[212:215], v[64:67]
	s_barrier
; #define PG8_STAGE(bufoff, gbase, voff) do { _Pragma("unroll") for (int _i = 0; _i < 2; ++_i) \
;         __builtin_amdgcn_global_load_lds((const unsigned*)((const char*)(gbase) + (voff)[_i]), (PG8_LAS unsigned*)(lds + (bufoff) + ldsw + _i * 8192), 16, 0, 0); } while (0)
; #define PG8_LDA(dst, b, h) do { if (PG8_MSK && !(mk & (3 << (2 * (h))))) break; _Pragma("unroll") for (int m = 0; m < 4; ++m) _Pragma("unroll") for (int k = 0; k < 2; ++k) dst[m][k] = *(const PG8_LAS bf16x8*)(lds + PG8_SA(b, h) + aoff + m * 2048 + k * 1024); } while (0)
; #define PG8_WAIT_V(n) asm volatile("s_waitcnt vmcnt(" #n ")" ::: "memory")
; #define PG8_WAIT_L(n) asm volatile("s_waitcnt lgkmcnt(" #n ")" ::: "memory")
; #define PG8_BAR __builtin_amdgcn_s_barrier()
; #define PG8_SCHED __builtin_amdgcn_sched_barrier(0)
; template <class Epi, class Sched, bool ALIGN_EPI = false, bool SP2 = false>
; __device__ __forceinline__ void gemm_phase(PG8_LAS unsigned char* lds, const Gemm g, const Sched& S, const Epi& E, const int tid) {
;     ...
;             PG8_LDA(At, 1, 1); PG8_STAGE(PG8_SB(1, 0), b3, voffB); PG8_STAGE(PG8_SB(1, 1), b3 + hstep, voffB); PG8_STAGE(PG8_SA(1, 0), a3, voffA);
;             PG8_WAIT_V(8); PG8_WAIT_L(0); PG8_BAR; PG8_MMA(1, 0, At, B0); PG8_MMA(1, 1, At, B1); PG8_BAR; PG8_SCHED;
	s_add_i32 s48, s65, s33
	v_lshl_add_u64 v[218:219], v[218:219], 0, s[34:35]
	s_mov_b32 m0, s48
	ds_read_b128 v[180:183], v147 offset:49152
	ds_read_b128 v[184:187], v147 offset:50176
	ds_read_b128 v[188:191], v147 offset:51200
	ds_read_b128 v[192:195], v147 offset:52224
	ds_read_b128 v[196:199], v147 offset:53248
	ds_read_b128 v[204:207], v147 offset:54272
	ds_read_b128 v[208:211], v147 offset:55296
	ds_read_b128 v[212:215], v147 offset:56320
	global_load_lds_dwordx4 v[218:219], off
	v_lshl_add_u64 v[218:219], v[220:221], 0, s[34:35]
	s_add_i32 m0, s48, 0x2000
	s_add_i32 s48, s66, s33
	global_load_lds_dwordx4 v[218:219], off
	v_lshl_add_u64 v[218:219], v[222:223], 0, s[34:35]
	s_mov_b32 m0, s48
	s_nop 0
	global_load_lds_dwordx4 v[218:219], off
	v_lshl_add_u64 v[218:219], v[224:225], 0, s[34:35]
	s_add_i32 m0, s48, 0x2000
	s_nop 0
	global_load_lds_dwordx4 v[218:219], off
	v_lshl_add_u64 v[218:219], v[226:227], 0, s[34:35]
	s_mov_b32 m0, s55
	s_nop 0
	global_load_lds_dwordx4 v[218:219], off
	v_lshl_add_u64 v[218:219], v[228:229], 0, s[34:35]
	s_mov_b32 m0, s56
	s_nop 0
	global_load_lds_dwordx4 v[218:219], off
	s_waitcnt vmcnt(8)
	s_waitcnt lgkmcnt(0)
	s_barrier
	s_waitcnt lgkmcnt(0)
	v_mfma_f32_16x16x32_bf16 v[60:63], v[148:151], v[180:183], v[60:63]
	v_mfma_f32_16x16x32_bf16 v[56:59], v[156:159], v[180:183], v[56:59]
	v_mfma_f32_16x16x32_bf16 v[44:47], v[148:151], v[188:191], v[44:47]
	v_mfma_f32_16x16x32_bf16 v[40:43], v[156:159], v[188:191], v[40:43]
	v_mfma_f32_16x16x32_bf16 v[28:31], v[148:151], v[196:199], v[28:31]
	v_mfma_f32_16x16x32_bf16 v[24:27], v[156:159], v[196:199], v[24:27]
	v_mfma_f32_16x16x32_bf16 v[12:15], v[148:151], v[208:211], v[12:15]
	v_mfma_f32_16x16x32_bf16 v[8:11], v[156:159], v[208:211], v[8:11]
	v_mfma_f32_16x16x32_bf16 v[60:63], v[152:155], v[184:187], v[60:63]
	v_mfma_f32_16x16x32_bf16 v[56:59], v[160:163], v[184:187], v[56:59]
	v_mfma_f32_16x16x32_bf16 v[44:47], v[152:155], v[192:195], v[44:47]
	v_mfma_f32_16x16x32_bf16 v[40:43], v[160:163], v[192:195], v[40:43]
	v_mfma_f32_16x16x32_bf16 v[28:31], v[152:155], v[204:207], v[28:31]
	v_mfma_f32_16x16x32_bf16 v[24:27], v[160:163], v[204:207], v[24:27]
	v_mfma_f32_16x16x32_bf16 v[12:15], v[152:155], v[212:215], v[12:15]
	v_mfma_f32_16x16x32_bf16 v[8:11], v[160:163], v[212:215], v[8:11]
	v_mfma_f32_16x16x32_bf16 v[52:55], v[164:167], v[180:183], v[52:55]
	v_mfma_f32_16x16x32_bf16 v[48:51], v[172:175], v[180:183], v[48:51]
	v_mfma_f32_16x16x32_bf16 v[36:39], v[164:167], v[188:191], v[36:39]
	v_mfma_f32_16x16x32_bf16 v[32:35], v[172:175], v[188:191], v[32:35]
	v_mfma_f32_16x16x32_bf16 v[20:23], v[164:167], v[196:199], v[20:23]
	v_mfma_f32_16x16x32_bf16 v[16:19], v[172:175], v[196:199], v[16:19]
	v_mfma_f32_16x16x32_bf16 v[4:7], v[164:167], v[208:211], v[4:7]
	v_mfma_f32_16x16x32_bf16 v[0:3], v[172:175], v[208:211], v[0:3]
	v_mfma_f32_16x16x32_bf16 v[52:55], v[168:171], v[184:187], v[52:55]
	v_mfma_f32_16x16x32_bf16 v[48:51], v[176:179], v[184:187], v[48:51]
	v_mfma_f32_16x16x32_bf16 v[36:39], v[168:171], v[192:195], v[36:39]
	v_mfma_f32_16x16x32_bf16 v[32:35], v[176:179], v[192:195], v[32:35]
	v_mfma_f32_16x16x32_bf16 v[20:23], v[168:171], v[204:207], v[20:23]
	v_mfma_f32_16x16x32_bf16 v[16:19], v[176:179], v[204:207], v[16:19]
	v_mfma_f32_16x16x32_bf16 v[4:7], v[168:171], v[212:215], v[4:7]
	v_mfma_f32_16x16x32_bf16 v[0:3], v[176:179], v[212:215], v[0:3]
	s_barrier
	s_add_u32 s46, s46, 0x100
	s_addc_u32 s47, s47, 0
	v_lshl_add_u64 v[144:145], v[144:145], 0, s[2:3]
	s_cmp_lt_u32 s64, s57
	v_lshl_add_u64 v[114:115], v[114:115], 0, s[2:3]
	s_cbranch_scc0 .LBB0_426
	s_mov_b32 s48, s64
	s_branch .LBB0_422

; #define PG8_STAGE(bufoff, gbase, voff) do { _Pragma("unroll") for (int _i = 0; _i < 2; ++_i) \
;         __builtin_amdgcn_global_load_lds((const unsigned*)((const char*)(gbase) + (voff)[_i]), (PG8_LAS unsigned*)(lds + (bufoff) + ldsw + _i * 8192), 16, 0, 0); } while (0)
; #define PG8_LDA(dst, b, h) do { if (PG8_MSK && !(mk & (3 << (2 * (h))))) break; _Pragma("unroll") for (int m = 0; m < 4; ++m) _Pragma("unroll") for (int k = 0; k < 2; ++k) dst[m][k] = *(const PG8_LAS bf16x8*)(lds + PG8_SA(b, h) + aoff + m * 2048 + k * 1024); } while (0)
; #define PG8_BAR __builtin_amdgcn_s_barrier()
; template <class Epi, class Sched, bool ALIGN_EPI = false, bool SP2 = false>
; __device__ __forceinline__ void gemm_phase(PG8_LAS unsigned char* lds, const Gemm g, const Sched& S, const Epi& E, const int tid) {
;     ...
;         for (int t = 0; t < nt; t += 2) {
;             const bool last = (t == nt - 2);
;             if constexpr (Epi::MID) { if (E.use_rs && t == (nt >> 1)) E.mid(acc, cur, wr, fr); }
;             const char* a1 = cA + (size_t)(t + 1) * kstep;
;             const char* a2 = last ? nA : cA + (size_t)(t + 2) * kstep; const char* b2 = last ? nB : cB + (size_t)(t + 2) * kstep;
;             const char* a3 = a2 + kstep; const char* b3 = b2 + kstep;
;             if (last && has_next) S.a_ready(nxt);
;             if constexpr (SP2) {
;             PG8_LDB(B0, 0, 0); PG8_LDB(B1, 0, 1); PG8_SCHED; PG8_LDA(At, 0, 0); PG8_STAGE(PG8_SA(1, 1), a1 + hstep, voffA);
;             PG8_WAIT_V(8); PG8_WAIT_L(0); PG8_BAR; PG8_MMA(0, 0, At, B0); PG8_MMA(0, 1, At, B1); PG8_BAR; PG8_SCHED;
;             PG8_LDA(At, 0, 1); PG8_STAGE(PG8_SB(0, 0), b2, voffB); PG8_STAGE(PG8_SB(0, 1), b2 + hstep, voffB); PG8_STAGE(PG8_SA(0, 0), a2, voffA);
;             PG8_WAIT_V(8); PG8_WAIT_L(0); PG8_BAR; PG8_MMA(1, 0, At, B0); PG8_MMA(1, 1, At, B1); PG8_BAR; PG8_SCHED;
;             PG8_LDB(B0, 1, 0); PG8_LDB(B1, 1, 1); PG8_SCHED; PG8_LDA(At, 1, 0); PG8_STAGE(PG8_SA(0, 1), a2 + hstep, voffA);
;             PG8_WAIT_V(8); PG8_WAIT_L(0); PG8_BAR; PG8_MMA(0, 0, At, B0); PG8_MMA(0, 1, At, B1); PG8_BAR; PG8_SCHED;
;             PG8_LDA(At, 1, 1); PG8_STAGE(PG8_SB(1, 0), b3, voffB); PG8_STAGE(PG8_SB(1, 1), b3 + hstep, voffB); PG8_STAGE(PG8_SA(1, 0), a3, voffA);
;             PG8_WAIT_V(8); PG8_WAIT_L(0); PG8_BAR; PG8_MMA(1, 0, At, B0); PG8_MMA(1, 1, At, B1); PG8_BAR; PG8_SCHED;
.LBB0_558:
	s_add_u32 s42, s40, 0xfff80080
	s_addc_u32 s43, s41, -1
	s_add_i32 s48, 0, 0x10000
	s_cmp_eq_u32 s30, 28
	s_cselect_b32 s45, s11, s43
	s_cselect_b32 s44, s14, s42
	v_add_u32_e32 v140, s48, v143
	s_cselect_b32 s43, s9, s27
	s_cselect_b32 s42, s15, s17
	s_add_i32 s50, 0, 0x14000
	ds_read_b128 v[146:149], v140
	ds_read_b128 v[150:153], v140 offset:1024
	ds_read_b128 v[154:157], v140 offset:2048
	ds_read_b128 v[158:161], v140 offset:3072
	v_add_u32_e32 v140, s50, v143
	ds_read_b128 v[162:165], v140
	ds_read_b128 v[166:169], v140 offset:1024
	ds_read_b128 v[170:173], v140 offset:2048
	ds_read_b128 v[174:177], v140 offset:3072
	v_lshl_add_u64 v[140:141], s[40:41], 0, v[136:137]
	s_add_i32 m0, s29, 0xc000
	ds_read_b128 v[178:181], v145
	ds_read_b128 v[182:185], v145 offset:1024
	ds_read_b128 v[186:189], v145 offset:2048
	ds_read_b128 v[190:193], v145 offset:3072
	ds_read_b128 v[194:197], v145 offset:4096
	ds_read_b128 v[204:207], v145 offset:5120
	ds_read_b128 v[208:211], v145 offset:6144
	ds_read_b128 v[212:215], v145 offset:7168
	global_load_lds_dwordx4 v[140:141], off
	v_lshl_add_u64 v[140:141], s[40:41], 0, v[138:139]
	s_add_i32 m0, s29, 0xe000
	s_nop 0
	global_load_lds_dwordx4 v[140:141], off
	s_waitcnt vmcnt(8)
	s_waitcnt lgkmcnt(0)
	s_barrier
	s_waitcnt lgkmcnt(0)
	v_mfma_f32_16x16x32_bf16 v[126:129], v[146:149], v[178:181], v[126:129]
	v_mfma_f32_16x16x32_bf16 v[118:121], v[154:157], v[178:181], v[118:121]
	v_mfma_f32_16x16x32_bf16 v[108:111], v[146:149], v[186:189], v[108:111]
	v_mfma_f32_16x16x32_bf16 v[100:103], v[154:157], v[186:189], v[100:103]
	v_mfma_f32_16x16x32_bf16 v[92:95], v[146:149], v[194:197], v[92:95]
	v_mfma_f32_16x16x32_bf16 v[84:87], v[154:157], v[194:197], v[84:87]
	v_mfma_f32_16x16x32_bf16 v[76:79], v[146:149], v[208:211], v[76:79]
	v_mfma_f32_16x16x32_bf16 v[68:71], v[154:157], v[208:211], v[68:71]
	v_mfma_f32_16x16x32_bf16 v[126:129], v[150:153], v[182:185], v[126:129]
	v_mfma_f32_16x16x32_bf16 v[118:121], v[158:161], v[182:185], v[118:121]
	v_mfma_f32_16x16x32_bf16 v[108:111], v[150:153], v[190:193], v[108:111]
	v_mfma_f32_16x16x32_bf16 v[100:103], v[158:161], v[190:193], v[100:103]
	v_mfma_f32_16x16x32_bf16 v[92:95], v[150:153], v[204:207], v[92:95]
	v_mfma_f32_16x16x32_bf16 v[84:87], v[158:161], v[204:207], v[84:87]
	v_mfma_f32_16x16x32_bf16 v[76:79], v[150:153], v[212:215], v[76:79]
	v_mfma_f32_16x16x32_bf16 v[68:71], v[158:161], v[212:215], v[68:71]
	v_mfma_f32_16x16x32_bf16 v[122:125], v[162:165], v[178:181], v[122:125]
	v_mfma_f32_16x16x32_bf16 v[114:117], v[170:173], v[178:181], v[114:117]
	v_mfma_f32_16x16x32_bf16 v[104:107], v[162:165], v[186:189], v[104:107]
	v_mfma_f32_16x16x32_bf16 v[96:99], v[170:173], v[186:189], v[96:99]
	v_mfma_f32_16x16x32_bf16 v[88:91], v[162:165], v[194:197], v[88:91]
	v_mfma_f32_16x16x32_bf16 v[80:83], v[170:173], v[194:197], v[80:83]
	v_mfma_f32_16x16x32_bf16 v[72:75], v[162:165], v[208:211], v[72:75]
	v_mfma_f32_16x16x32_bf16 v[64:67], v[170:173], v[208:211], v[64:67]
	v_mfma_f32_16x16x32_bf16 v[122:125], v[166:169], v[182:185], v[122:125]
	v_mfma_f32_16x16x32_bf16 v[114:117], v[174:177], v[182:185], v[114:117]
	v_mfma_f32_16x16x32_bf16 v[104:107], v[166:169], v[190:193], v[104:107]
	v_mfma_f32_16x16x32_bf16 v[96:99], v[174:177], v[190:193], v[96:99]
	v_mfma_f32_16x16x32_bf16 v[88:91], v[166:169], v[204:207], v[88:91]
	v_mfma_f32_16x16x32_bf16 v[80:83], v[174:177], v[204:207], v[80:83]
	v_mfma_f32_16x16x32_bf16 v[72:75], v[166:169], v[212:215], v[72:75]
	v_mfma_f32_16x16x32_bf16 v[64:67], v[174:177], v[212:215], v[64:67]
	s_barrier
	s_add_i32 s48, s48, s33
	v_lshl_add_u64 v[140:141], s[42:43], 0, v[112:113]
	s_mov_b32 m0, s48
	ds_read_b128 v[178:181], v145 offset:16384
	ds_read_b128 v[182:185], v145 offset:17408
	ds_read_b128 v[186:189], v145 offset:18432
	ds_read_b128 v[190:193], v145 offset:19456
	ds_read_b128 v[194:197], v145 offset:20480
	ds_read_b128 v[204:207], v145 offset:21504
	ds_read_b128 v[208:211], v145 offset:22528
	ds_read_b128 v[212:215], v145 offset:23552
	global_load_lds_dwordx4 v[140:141], off
	s_add_i32 m0, s48, 0x2000
	s_add_u32 s48, s42, 0x80000
	v_lshl_add_u64 v[198:199], s[42:43], 0, v[134:135]
	s_addc_u32 s49, s43, 0
	s_add_i32 s50, s50, s33
	global_load_lds_dwordx4 v[198:199], off
	v_lshl_add_u64 v[216:217], s[48:49], 0, v[112:113]
	s_mov_b32 m0, s50
	v_lshl_add_u64 v[218:219], s[44:45], 0, v[132:133]
	global_load_lds_dwordx4 v[216:217], off
	v_lshl_add_u64 v[216:217], s[48:49], 0, v[134:135]
	s_add_i32 m0, s50, 0x2000
	s_nop 0
	global_load_lds_dwordx4 v[216:217], off
	v_lshl_add_u64 v[216:217], s[44:45], 0, v[130:131]
	s_mov_b32 m0, s29
	s_nop 0
	global_load_lds_dwordx4 v[216:217], off
	s_mov_b32 m0, s36
	s_nop 0
	global_load_lds_dwordx4 v[218:219], off
	s_waitcnt vmcnt(8)
	s_waitcnt lgkmcnt(0)
	s_barrier
; #define PG8_STAGE(bufoff, gbase, voff) do { _Pragma("unroll") for (int _i = 0; _i < 2; ++_i) \
;         __builtin_amdgcn_global_load_lds((const unsigned*)((const char*)(gbase) + (voff)[_i]), (PG8_LAS unsigned*)(lds + (bufoff) + ldsw + _i * 8192), 16, 0, 0); } while (0)
; #define PG8_LDA(dst, b, h) do { if (PG8_MSK && !(mk & (3 << (2 * (h))))) break; _Pragma("unroll") for (int m = 0; m < 4; ++m) _Pragma("unroll") for (int k = 0; k < 2; ++k) dst[m][k] = *(const PG8_LAS bf16x8*)(lds + PG8_SA(b, h) + aoff + m * 2048 + k * 1024); } while (0)
; #define PG8_LDB(dst, b, h) do { if (PG8_MSK && !(mk & (5 << (h)))) break; _Pragma("unroll") for (int n = 0; n < 2; ++n) _Pragma("unroll") for (int k = 0; k < 2; ++k) dst[n][k] = *(const PG8_LAS bf16x8*)(lds + PG8_SB(b, h) + boff + n * 2048 + k * 1024); } while (0)
; #define PG8_WAIT_V(n) asm volatile("s_waitcnt vmcnt(" #n ")" ::: "memory")
; #define PG8_WAIT_L(n) asm volatile("s_waitcnt lgkmcnt(" #n ")" ::: "memory")
; #define PG8_BAR __builtin_amdgcn_s_barrier()
; #define PG8_SCHED __builtin_amdgcn_sched_barrier(0)
; template <class Epi, class Sched, bool ALIGN_EPI = false, bool SP2 = false>
; __device__ __forceinline__ void gemm_phase(PG8_LAS unsigned char* lds, const Gemm g, const Sched& S, const Epi& E, const int tid) {
;     ...
;             PG8_WAIT_V(8); PG8_WAIT_L(0); PG8_BAR; PG8_MMA(0, 0, At, B0); PG8_MMA(0, 1, At, B1); PG8_BAR; PG8_SCHED;
;             PG8_LDA(At, 0, 1); PG8_STAGE(PG8_SB(0, 0), b2, voffB); PG8_STAGE(PG8_SB(0, 1), b2 + hstep, voffB); PG8_STAGE(PG8_SA(0, 0), a2, voffA);
;             PG8_WAIT_V(8); PG8_WAIT_L(0); PG8_BAR; PG8_MMA(1, 0, At, B0); PG8_MMA(1, 1, At, B1); PG8_BAR; PG8_SCHED;
;             PG8_LDB(B0, 1, 0); PG8_LDB(B1, 1, 1); PG8_SCHED; PG8_LDA(At, 1, 0); PG8_STAGE(PG8_SA(0, 1), a2 + hstep, voffA);
;             PG8_WAIT_V(8); PG8_WAIT_L(0); PG8_BAR; PG8_MMA(0, 0, At, B0); PG8_MMA(0, 1, At, B1); PG8_BAR; PG8_SCHED;
	s_waitcnt lgkmcnt(0)
	v_mfma_f32_16x16x32_bf16 v[60:63], v[146:149], v[178:181], v[60:63]
	v_mfma_f32_16x16x32_bf16 v[52:55], v[154:157], v[178:181], v[52:55]
	v_mfma_f32_16x16x32_bf16 v[44:47], v[146:149], v[186:189], v[44:47]
	v_mfma_f32_16x16x32_bf16 v[36:39], v[154:157], v[186:189], v[36:39]
	v_mfma_f32_16x16x32_bf16 v[28:31], v[146:149], v[194:197], v[28:31]
	v_mfma_f32_16x16x32_bf16 v[20:23], v[154:157], v[194:197], v[20:23]
	v_mfma_f32_16x16x32_bf16 v[12:15], v[146:149], v[208:211], v[12:15]
	v_mfma_f32_16x16x32_bf16 v[4:7], v[154:157], v[208:211], v[4:7]
	v_mfma_f32_16x16x32_bf16 v[60:63], v[150:153], v[182:185], v[60:63]
	v_mfma_f32_16x16x32_bf16 v[52:55], v[158:161], v[182:185], v[52:55]
	v_mfma_f32_16x16x32_bf16 v[44:47], v[150:153], v[190:193], v[44:47]
	v_mfma_f32_16x16x32_bf16 v[36:39], v[158:161], v[190:193], v[36:39]
	v_mfma_f32_16x16x32_bf16 v[28:31], v[150:153], v[204:207], v[28:31]
	v_mfma_f32_16x16x32_bf16 v[20:23], v[158:161], v[204:207], v[20:23]
	v_mfma_f32_16x16x32_bf16 v[12:15], v[150:153], v[212:215], v[12:15]
	v_mfma_f32_16x16x32_bf16 v[4:7], v[158:161], v[212:215], v[4:7]
	v_mfma_f32_16x16x32_bf16 v[56:59], v[162:165], v[178:181], v[56:59]
	v_mfma_f32_16x16x32_bf16 v[48:51], v[170:173], v[178:181], v[48:51]
	v_mfma_f32_16x16x32_bf16 v[40:43], v[162:165], v[186:189], v[40:43]
	v_mfma_f32_16x16x32_bf16 v[32:35], v[170:173], v[186:189], v[32:35]
	v_mfma_f32_16x16x32_bf16 v[24:27], v[162:165], v[194:197], v[24:27]
	v_mfma_f32_16x16x32_bf16 v[16:19], v[170:173], v[194:197], v[16:19]
	v_mfma_f32_16x16x32_bf16 v[8:11], v[162:165], v[208:211], v[8:11]
	v_mfma_f32_16x16x32_bf16 v[0:3], v[170:173], v[208:211], v[0:3]
	v_mfma_f32_16x16x32_bf16 v[56:59], v[166:169], v[182:185], v[56:59]
	v_mfma_f32_16x16x32_bf16 v[48:51], v[174:177], v[182:185], v[48:51]
	v_mfma_f32_16x16x32_bf16 v[40:43], v[166:169], v[190:193], v[40:43]
	v_mfma_f32_16x16x32_bf16 v[32:35], v[174:177], v[190:193], v[32:35]
	v_mfma_f32_16x16x32_bf16 v[24:27], v[166:169], v[204:207], v[24:27]
	v_mfma_f32_16x16x32_bf16 v[16:19], v[174:177], v[204:207], v[16:19]
	v_mfma_f32_16x16x32_bf16 v[8:11], v[166:169], v[212:215], v[8:11]
	v_mfma_f32_16x16x32_bf16 v[0:3], v[174:177], v[212:215], v[0:3]
	s_barrier
	s_add_i32 s48, 0, 0x18000
	s_add_i32 s49, 0, 0x1c000
	v_add_u32_e32 v158, s48, v143
	v_add_u32_e32 v174, s49, v143
	ds_read_b128 v[146:149], v158
	ds_read_b128 v[150:153], v158 offset:1024
	ds_read_b128 v[154:157], v158 offset:2048
	ds_read_b128 v[158:161], v158 offset:3072
	ds_read_b128 v[162:165], v174
	ds_read_b128 v[166:169], v174 offset:1024
	ds_read_b128 v[170:173], v174 offset:2048
	ds_read_b128 v[174:177], v174 offset:3072
	s_add_u32 s44, s44, 0x80000
	s_addc_u32 s45, s45, 0
	s_mov_b32 m0, s37
	v_lshl_add_u64 v[220:221], s[44:45], 0, v[130:131]
	ds_read_b128 v[178:181], v145 offset:32768
	ds_read_b128 v[182:185], v145 offset:33792
	ds_read_b128 v[186:189], v145 offset:34816
	ds_read_b128 v[190:193], v145 offset:35840
	ds_read_b128 v[194:197], v145 offset:36864
	ds_read_b128 v[204:207], v145 offset:37888
	ds_read_b128 v[208:211], v145 offset:38912
	ds_read_b128 v[212:215], v145 offset:39936
	global_load_lds_dwordx4 v[220:221], off
	v_lshl_add_u64 v[220:221], s[44:45], 0, v[132:133]
	s_mov_b32 m0, s38
	s_nop 0
	global_load_lds_dwordx4 v[220:221], off
	s_waitcnt vmcnt(8)
	s_waitcnt lgkmcnt(0)
	s_barrier
	s_waitcnt lgkmcnt(0)
	v_mfma_f32_16x16x32_bf16 v[126:129], v[146:149], v[178:181], v[126:129]
	v_mfma_f32_16x16x32_bf16 v[118:121], v[154:157], v[178:181], v[118:121]
	v_mfma_f32_16x16x32_bf16 v[108:111], v[146:149], v[186:189], v[108:111]
	v_mfma_f32_16x16x32_bf16 v[100:103], v[154:157], v[186:189], v[100:103]
	v_mfma_f32_16x16x32_bf16 v[92:95], v[146:149], v[194:197], v[92:95]
	v_mfma_f32_16x16x32_bf16 v[84:87], v[154:157], v[194:197], v[84:87]
	v_mfma_f32_16x16x32_bf16 v[76:79], v[146:149], v[208:211], v[76:79]
	v_mfma_f32_16x16x32_bf16 v[68:71], v[154:157], v[208:211], v[68:71]
	v_mfma_f32_16x16x32_bf16 v[126:129], v[150:153], v[182:185], v[126:129]
	v_mfma_f32_16x16x32_bf16 v[118:121], v[158:161], v[182:185], v[118:121]
	v_mfma_f32_16x16x32_bf16 v[108:111], v[150:153], v[190:193], v[108:111]
	v_mfma_f32_16x16x32_bf16 v[100:103], v[158:161], v[190:193], v[100:103]
	v_mfma_f32_16x16x32_bf16 v[92:95], v[150:153], v[204:207], v[92:95]
	v_mfma_f32_16x16x32_bf16 v[84:87], v[158:161], v[204:207], v[84:87]
	v_mfma_f32_16x16x32_bf16 v[76:79], v[150:153], v[212:215], v[76:79]
	v_mfma_f32_16x16x32_bf16 v[68:71], v[158:161], v[212:215], v[68:71]
	v_mfma_f32_16x16x32_bf16 v[122:125], v[162:165], v[178:181], v[122:125]
	v_mfma_f32_16x16x32_bf16 v[114:117], v[170:173], v[178:181], v[114:117]
	v_mfma_f32_16x16x32_bf16 v[104:107], v[162:165], v[186:189], v[104:107]
	v_mfma_f32_16x16x32_bf16 v[96:99], v[170:173], v[186:189], v[96:99]
	v_mfma_f32_16x16x32_bf16 v[88:91], v[162:165], v[194:197], v[88:91]
	v_mfma_f32_16x16x32_bf16 v[80:83], v[170:173], v[194:197], v[80:83]
	v_mfma_f32_16x16x32_bf16 v[72:75], v[162:165], v[208:211], v[72:75]
	v_mfma_f32_16x16x32_bf16 v[64:67], v[170:173], v[208:211], v[64:67]
	v_mfma_f32_16x16x32_bf16 v[122:125], v[166:169], v[182:185], v[122:125]
	v_mfma_f32_16x16x32_bf16 v[114:117], v[174:177], v[182:185], v[114:117]
	v_mfma_f32_16x16x32_bf16 v[104:107], v[166:169], v[190:193], v[104:107]
	v_mfma_f32_16x16x32_bf16 v[96:99], v[174:177], v[190:193], v[96:99]
	v_mfma_f32_16x16x32_bf16 v[88:91], v[166:169], v[204:207], v[88:91]
	v_mfma_f32_16x16x32_bf16 v[80:83], v[174:177], v[204:207], v[80:83]
	v_mfma_f32_16x16x32_bf16 v[72:75], v[166:169], v[212:215], v[72:75]
	v_mfma_f32_16x16x32_bf16 v[64:67], v[174:177], v[212:215], v[64:67]
	s_barrier
; #define PG8_STAGE(bufoff, gbase, voff) do { _Pragma("unroll") for (int _i = 0; _i < 2; ++_i) \
;         __builtin_amdgcn_global_load_lds((const unsigned*)((const char*)(gbase) + (voff)[_i]), (PG8_LAS unsigned*)(lds + (bufoff) + ldsw + _i * 8192), 16, 0, 0); } while (0)
; #define PG8_LDA(dst, b, h) do { if (PG8_MSK && !(mk & (3 << (2 * (h))))) break; _Pragma("unroll") for (int m = 0; m < 4; ++m) _Pragma("unroll") for (int k = 0; k < 2; ++k) dst[m][k] = *(const PG8_LAS bf16x8*)(lds + PG8_SA(b, h) + aoff + m * 2048 + k * 1024); } while (0)
; #define PG8_BAR __builtin_amdgcn_s_barrier()
; template <class Epi, class Sched, bool ALIGN_EPI = false, bool SP2 = false>
; __device__ __forceinline__ void gemm_phase(PG8_LAS unsigned char* lds, const Gemm g, const Sched& S, const Epi& E, const int tid) {
;     ...
;         for (int t = 0; t < nt; t += 2) {
;             const bool last = (t == nt - 2);
;             if constexpr (Epi::MID) { if (E.use_rs && t == (nt >> 1)) E.mid(acc, cur, wr, fr); }
;             const char* a1 = cA + (size_t)(t + 1) * kstep;
;             const char* a2 = last ? nA : cA + (size_t)(t + 2) * kstep; const char* b2 = last ? nB : cB + (size_t)(t + 2) * kstep;
;             const char* a3 = a2 + kstep; const char* b3 = b2 + kstep;
;             if (last && has_next) S.a_ready(nxt);
;             if constexpr (SP2) {
;             PG8_LDB(B0, 0, 0); PG8_LDB(B1, 0, 1); PG8_SCHED; PG8_LDA(At, 0, 0); PG8_STAGE(PG8_SA(1, 1), a1 + hstep, voffA);
;             PG8_WAIT_V(8); PG8_WAIT_L(0); PG8_BAR; PG8_MMA(0, 0, At, B0); PG8_MMA(0, 1, At, B1); PG8_BAR; PG8_SCHED;
;             PG8_LDA(At, 0, 1); PG8_STAGE(PG8_SB(0, 0), b2, voffB); PG8_STAGE(PG8_SB(0, 1), b2 + hstep, voffB); PG8_STAGE(PG8_SA(0, 0), a2, voffA);
;             PG8_WAIT_V(8); PG8_WAIT_L(0); PG8_BAR; PG8_MMA(1, 0, At, B0); PG8_MMA(1, 1, At, B1); PG8_BAR; PG8_SCHED;
;             PG8_LDB(B0, 1, 0); PG8_LDB(B1, 1, 1); PG8_SCHED; PG8_LDA(At, 1, 0); PG8_STAGE(PG8_SA(0, 1), a2 + hstep, voffA);
;             PG8_WAIT_V(8); PG8_WAIT_L(0); PG8_BAR; PG8_MMA(0, 0, At, B0); PG8_MMA(0, 1, At, B1); PG8_BAR; PG8_SCHED;
;             PG8_LDA(At, 1, 1); PG8_STAGE(PG8_SB(1, 0), b3, voffB); PG8_STAGE(PG8_SB(1, 1), b3 + hstep, voffB); PG8_STAGE(PG8_SA(1, 0), a3, voffA);
;             PG8_WAIT_V(8); PG8_WAIT_L(0); PG8_BAR; PG8_MMA(1, 0, At, B0); PG8_MMA(1, 1, At, B1); PG8_BAR; PG8_SCHED;
	s_add_i32 s44, s48, s33
	v_lshl_add_u64 v[140:141], v[140:141], 0, s[34:35]
	s_mov_b32 m0, s44
	ds_read_b128 v[178:181], v145 offset:49152
	ds_read_b128 v[182:185], v145 offset:50176
	ds_read_b128 v[186:189], v145 offset:51200
	ds_read_b128 v[190:193], v145 offset:52224
	ds_read_b128 v[194:197], v145 offset:53248
	ds_read_b128 v[204:207], v145 offset:54272
	ds_read_b128 v[208:211], v145 offset:55296
	ds_read_b128 v[212:215], v145 offset:56320
	global_load_lds_dwordx4 v[140:141], off
	s_add_i32 m0, s44, 0x2000
	s_add_u32 s42, s42, 0x80080
	v_lshl_add_u64 v[140:141], v[198:199], 0, s[34:35]
	s_addc_u32 s43, s43, 0
	s_add_i32 s44, s49, s33
	global_load_lds_dwordx4 v[140:141], off
	v_lshl_add_u64 v[140:141], s[42:43], 0, v[112:113]
	s_mov_b32 m0, s44
	s_nop 0
	global_load_lds_dwordx4 v[140:141], off
	v_lshl_add_u64 v[140:141], s[42:43], 0, v[134:135]
	s_add_i32 m0, s44, 0x2000
	s_nop 0
	global_load_lds_dwordx4 v[140:141], off
	v_lshl_add_u64 v[140:141], v[216:217], 0, s[34:35]
	s_mov_b32 m0, s39
	s_nop 0
	global_load_lds_dwordx4 v[140:141], off
	v_lshl_add_u64 v[140:141], v[218:219], 0, s[34:35]
	s_mov_b32 m0, s46
	s_nop 0
	global_load_lds_dwordx4 v[140:141], off
	s_waitcnt vmcnt(8)
	s_waitcnt lgkmcnt(0)
	s_barrier
	s_waitcnt lgkmcnt(0)
	v_mfma_f32_16x16x32_bf16 v[60:63], v[146:149], v[178:181], v[60:63]
	v_mfma_f32_16x16x32_bf16 v[52:55], v[154:157], v[178:181], v[52:55]
	v_mfma_f32_16x16x32_bf16 v[44:47], v[146:149], v[186:189], v[44:47]
	v_mfma_f32_16x16x32_bf16 v[36:39], v[154:157], v[186:189], v[36:39]
	v_mfma_f32_16x16x32_bf16 v[28:31], v[146:149], v[194:197], v[28:31]
	v_mfma_f32_16x16x32_bf16 v[20:23], v[154:157], v[194:197], v[20:23]
	v_mfma_f32_16x16x32_bf16 v[12:15], v[146:149], v[208:211], v[12:15]
	v_mfma_f32_16x16x32_bf16 v[4:7], v[154:157], v[208:211], v[4:7]
	v_mfma_f32_16x16x32_bf16 v[60:63], v[150:153], v[182:185], v[60:63]
	v_mfma_f32_16x16x32_bf16 v[52:55], v[158:161], v[182:185], v[52:55]
	v_mfma_f32_16x16x32_bf16 v[44:47], v[150:153], v[190:193], v[44:47]
	v_mfma_f32_16x16x32_bf16 v[36:39], v[158:161], v[190:193], v[36:39]
	v_mfma_f32_16x16x32_bf16 v[28:31], v[150:153], v[204:207], v[28:31]
	v_mfma_f32_16x16x32_bf16 v[20:23], v[158:161], v[204:207], v[20:23]
	v_mfma_f32_16x16x32_bf16 v[12:15], v[150:153], v[212:215], v[12:15]
	v_mfma_f32_16x16x32_bf16 v[4:7], v[158:161], v[212:215], v[4:7]
	v_mfma_f32_16x16x32_bf16 v[56:59], v[162:165], v[178:181], v[56:59]
	v_mfma_f32_16x16x32_bf16 v[48:51], v[170:173], v[178:181], v[48:51]
	v_mfma_f32_16x16x32_bf16 v[40:43], v[162:165], v[186:189], v[40:43]
	v_mfma_f32_16x16x32_bf16 v[32:35], v[170:173], v[186:189], v[32:35]
	v_mfma_f32_16x16x32_bf16 v[24:27], v[162:165], v[194:197], v[24:27]
	v_mfma_f32_16x16x32_bf16 v[16:19], v[170:173], v[194:197], v[16:19]
	v_mfma_f32_16x16x32_bf16 v[8:11], v[162:165], v[208:211], v[8:11]
	v_mfma_f32_16x16x32_bf16 v[0:3], v[170:173], v[208:211], v[0:3]
	v_mfma_f32_16x16x32_bf16 v[56:59], v[166:169], v[182:185], v[56:59]
	v_mfma_f32_16x16x32_bf16 v[48:51], v[174:177], v[182:185], v[48:51]
	v_mfma_f32_16x16x32_bf16 v[40:43], v[166:169], v[190:193], v[40:43]
	v_mfma_f32_16x16x32_bf16 v[32:35], v[174:177], v[190:193], v[32:35]
	v_mfma_f32_16x16x32_bf16 v[24:27], v[166:169], v[204:207], v[24:27]
	v_mfma_f32_16x16x32_bf16 v[16:19], v[174:177], v[204:207], v[16:19]
	v_mfma_f32_16x16x32_bf16 v[8:11], v[166:169], v[212:215], v[8:11]
	v_mfma_f32_16x16x32_bf16 v[0:3], v[174:177], v[212:215], v[0:3]
	s_barrier
	s_add_i32 s30, s30, 2
	s_add_u32 s40, s40, 0x100
	s_addc_u32 s41, s41, 0
	s_add_u32 s17, s17, 0x100
	s_addc_u32 s27, s27, 0
	s_cmp_lt_u32 s30, 30
	s_cbranch_scc1 .LBB0_558
	s_andn2_b64 vcc, exec, s[6:7]
	v_readlane_b32 s27, v254, 25
	s_mov_b32 s30, 0x9000
	s_cbranch_vccnz .LBB0_561
	s_barrier
